# GEMM tile order WGM 4->8 for P1 and P7 (8 pm x 4 pn per XCD round); otherwise as v16
# baseline (speedup 1.0000x reference)
; #define LAS __attribute__((address_space(3)))
; __device__ __forceinline__ unsigned xb_ld(unsigned* p)              { return __hip_atomic_load(p, __ATOMIC_RELAXED, __HIP_MEMORY_SCOPE_AGENT); }
; __device__ __forceinline__ void xcd_barrier_complete(unsigned* bar, unsigned x, unsigned& nloc, unsigned& nx) {
;     ...
;         sum = 0u; cnt = 0u; mine = 0u;
; #pragma unroll
;         for (unsigned j = 0; j < 16; ++j) { const unsigned c = xb_ld(&bar[XB_XCNT(j)]); sum += c; cnt += (c > 0u) ? 1u : 0u; mine = (j == x) ? c : mine; }
;         if (sum == G) break;
; __global__ void __launch_bounds__(NTHR, 2) fwd_megakernel(Args args) {
;     ...
;     const int tid0 = threadIdx.x, wave = __builtin_amdgcn_readfirstlane(tid0 >> 6);
;     ...
;     const int G = gridDim.x, bid = blockIdx.x, gw = bid * NWAVES + wave, NGW = G * NWAVES;
;     unsigned char* ws = args.ws;
;     float* rn2 = (float*)(ws + WS_RN2);
;     float* logf = (float*)(ws + WS_LOGF); float* cs = (float*)(ws + WS_CS);
;     bf16* Win_t = (bf16*)(ws + WS_WIN); bf16* Wc_t = (bf16*)(ws + WS_WC); bf16* Wa_t = (bf16*)(ws + WS_WA); bf16* Wmix_t = (bf16*)(ws + WS_WMIX);
;     bf16* W1_t = (bf16*)(ws + WS_W1); bf16* W2_t = (bf16*)(ws + WS_W2);
;     bf16* Z = (bf16*)(ws + WS_Z); bf16* XN = (bf16*)(ws + WS_XN); bf16* CONVY = (bf16*)(ws + WS_CONVY); bf16* ATTO = (bf16*)(ws + WS_ATTO);
;     bf16* XG = (bf16*)(ws + WS_Z + 256 * MiB);
;     float* rowss = (float*)(ws + WS_RSS);
;     float* xres = args.out;
;     volatile LAS unsigned* bst = (volatile LAS unsigned*)(L + att::LDS_BYTES + 65536 + 64);
;     if (tid0 < 2) bst[tid0] = 0u;
;     __syncthreads();
;     const XcdBarrier xbar = xcd_barrier_post((unsigned*)(ws + WS_BAR), bst);
.LBB0_5:
	s_or_b64 exec, exec, s[0:1]
	s_lshr_b32 s97, s6, 6
	s_lshl_b32 s0, s2, 3
	s_add_i32 s24, s97, s0
	s_lshl_b32 s80, s70, 3
	s_add_u32 s88, s68, 0x24000000
	s_addc_u32 s89, s69, 0
	s_add_u32 s18, s68, 0x100000
	s_addc_u32 s19, s69, 0
	s_add_u32 s20, s68, 0x180000
	s_addc_u32 s21, s69, 0
	s_add_u32 s26, s68, 0x200000
	s_addc_u32 s27, s69, 0
	s_add_u32 s28, s68, 0x2a00000
	s_addc_u32 s29, s69, 0
	s_add_u32 s30, s68, 0x2e00000
	s_addc_u32 s31, s69, 0
	s_add_u32 s34, s68, 0x3200000
	s_addc_u32 s35, s69, 0
	s_add_u32 s36, s68, 0x3a00000
	s_addc_u32 s37, s69, 0
	s_add_u32 s38, s68, 0x5a00000
	s_addc_u32 s39, s69, 0
	s_add_u32 s4, s68, 0x8000000
	s_addc_u32 s5, s69, 0
	s_add_u32 s6, s68, 0x1c000000
	s_addc_u32 s7, s69, 0
	s_add_u32 s8, s68, 0x20000000
	s_addc_u32 s9, s69, 0
	s_add_u32 s42, s68, 0x22000000
	s_addc_u32 s43, s69, 0
	s_add_u32 s10, s68, 0x18000000
	s_addc_u32 s11, s69, 0
	s_add_u32 s12, s68, 0x20000
	s_addc_u32 s13, s69, 0
	s_cmpk_lt_i32 s2, 0x100
	s_cselect_b64 s[0:1], -1, 0
	v_writelane_b32 v252, s0, 26
	v_lshrrev_b32_e32 v1, 20, v0
	v_lshrrev_b32_e32 v0, 10, v0
	v_writelane_b32 v252, s1, 27
	s_lshl_b32 s0, s97, 14
	s_add_i32 s0, s0, 0
	s_cmpk_lt_i32 s24, 0x7800
	v_writelane_b32 v252, s0, 28
	s_cselect_b64 s[0:1], -1, 0
	v_writelane_b32 v252, s0, 29
	s_ashr_i32 s25, s24, 31
	v_or_b32_e32 v0, v0, v1
	v_writelane_b32 v252, s1, 30
	s_lshl_b64 s[0:1], s[24:25], 13
	v_writelane_b32 v252, s0, 31
	s_cmpk_lt_i32 s24, 0x4000
	s_mul_i32 s71, s71, s70
	v_writelane_b32 v252, s1, 32
	s_cselect_b64 s[0:1], -1, 0
	v_writelane_b32 v252, s0, 33
	s_mul_i32 s71, s71, s16
	v_mbcnt_lo_u32_b32 v1, -1, 0
	v_writelane_b32 v252, s1, 34
	s_add_u32 s0, s68, 0x4200
	s_addc_u32 s1, s69, 0
	v_writelane_b32 v252, s0, 35
	v_mov_b32_e32 v193, 0
	v_mov_b32_e32 v237, 0x358637bd
	v_writelane_b32 v252, s1, 36
	s_add_u32 s0, s68, 0x4400
	s_addc_u32 s1, s69, 0
	v_writelane_b32 v252, s0, 37
	v_mov_b32_e32 v206, 0x260
	v_mbcnt_hi_u32_b32 v203, -1, v1
	v_writelane_b32 v252, s1, 38
	s_add_u32 s0, s68, 0x4500
	s_addc_u32 s1, s69, 0
	v_writelane_b32 v252, s0, 39
	v_mov_b32_e32 v207, 0xff800000
	v_mov_b32_e32 v208, 0x5000
	v_writelane_b32 v252, s1, 40
	s_add_u32 s0, s68, 0x4600
	s_addc_u32 s1, s69, 0
	v_writelane_b32 v252, s0, 41
	v_mov_b64_e32 v[232:233], 0x200
	v_mov_b64_e32 v[204:205], 0x1ff
	v_writelane_b32 v252, s1, 42
	s_add_u32 s0, s68, 0x4700
	s_addc_u32 s1, s69, 0
	v_writelane_b32 v252, s0, 43
	v_mov_b64_e32 v[250:251], 0x7ff
	s_movk_i32 s61, 0x4000
	v_writelane_b32 v252, s1, 44
	s_add_u32 s0, s68, 0x4800
	s_addc_u32 s1, s69, 0
	v_writelane_b32 v252, s0, 45
	s_movk_i32 s81, 0x7fff
	s_mov_b32 s96, 0xffff0000
	v_writelane_b32 v252, s1, 46
	s_add_u32 s0, s68, 0x4900
	s_addc_u32 s1, s69, 0
	v_writelane_b32 v252, s0, 47
	s_movk_i32 s84, 0x1000
	s_movk_i32 s85, 0x5000
	v_writelane_b32 v252, s1, 48
	s_add_u32 s0, s68, 0x4a00
	s_addc_u32 s1, s69, 0
	v_writelane_b32 v252, s0, 49
	s_mov_b32 s90, 0x42000000
	s_mov_b32 s60, 0x3e0293ee
	v_writelane_b32 v252, s1, 50
	s_add_u32 s0, s68, 0x4b00
	s_addc_u32 s1, s69, 0
	v_writelane_b32 v252, s0, 51
	s_nop 1
	v_writelane_b32 v252, s1, 52
	s_add_u32 s0, s68, 0x4c00
	s_addc_u32 s1, s69, 0
	v_writelane_b32 v252, s0, 53
	s_nop 1
	v_writelane_b32 v252, s1, 54
	s_add_u32 s0, s68, 0x4d00
	s_addc_u32 s1, s69, 0
	s_add_u32 s82, s68, 0x4e00
	v_writelane_b32 v252, s0, 55
	s_addc_u32 s83, s69, 0
	s_nop 0
	v_writelane_b32 v252, s1, 56
	s_add_u32 s0, s68, 0x4f00
	s_addc_u32 s1, s69, 0
	s_add_u32 s72, s68, 0x5000
	s_addc_u32 s73, s69, 0
	s_add_u32 s74, s68, 0x5100
	s_addc_u32 s75, s69, 0
	s_add_u32 s76, s68, 0x5200
	s_addc_u32 s77, s69, 0
	s_add_u32 s78, s68, 0x5300
	s_addc_u32 s79, s69, 0
	s_cmp_eq_u32 s3, 15
	s_cselect_b64 s[22:23], -1, 0
	v_writelane_b32 v252, s22, 57
	s_cmp_eq_u32 s3, 14
	s_nop 0
	v_writelane_b32 v252, s23, 58
	s_cselect_b64 s[22:23], -1, 0
	v_writelane_b32 v252, s22, 59
	s_cmp_eq_u32 s3, 13
	s_nop 0
	v_writelane_b32 v252, s23, 60
	s_cselect_b64 s[22:23], -1, 0
	v_writelane_b32 v252, s22, 61
	s_cmp_eq_u32 s3, 12
	s_nop 0
	v_writelane_b32 v252, s23, 62
	s_cselect_b64 s[22:23], -1, 0
	v_writelane_b32 v252, s22, 63
	s_cmp_eq_u32 s3, 11
	s_nop 0
	v_writelane_b32 v253, s23, 0
	s_cselect_b64 s[22:23], -1, 0
	v_writelane_b32 v253, s22, 1
	s_cmp_eq_u32 s3, 10
	s_nop 0
	v_writelane_b32 v253, s23, 2
	s_cselect_b64 s[22:23], -1, 0
	v_writelane_b32 v253, s22, 3
	s_cmp_eq_u32 s3, 9
	s_nop 0
	v_writelane_b32 v253, s23, 4
	s_cselect_b64 s[22:23], -1, 0
	v_writelane_b32 v253, s22, 5
	s_cmp_eq_u32 s3, 8
	s_nop 0
	v_writelane_b32 v253, s23, 6
	s_cselect_b64 s[22:23], -1, 0
	v_writelane_b32 v253, s22, 7
	s_cmp_eq_u32 s3, 7
	s_nop 0
	v_writelane_b32 v253, s23, 8
	s_cselect_b64 s[22:23], -1, 0
	v_writelane_b32 v253, s22, 9
	s_cmp_eq_u32 s3, 6
	s_nop 0
	v_writelane_b32 v253, s23, 10
	s_cselect_b64 s[22:23], -1, 0
	v_writelane_b32 v253, s22, 11
	s_cmp_eq_u32 s3, 5
	s_nop 0
	v_writelane_b32 v253, s23, 12
	s_cselect_b64 s[22:23], -1, 0
	v_writelane_b32 v253, s22, 13
	s_cmp_eq_u32 s3, 4
	s_nop 0
	v_writelane_b32 v253, s23, 14
	s_cselect_b64 s[22:23], -1, 0
	v_writelane_b32 v253, s22, 15
	s_cmp_eq_u32 s3, 3
	s_nop 0
	v_writelane_b32 v253, s23, 16
	s_cselect_b64 s[22:23], -1, 0
	v_writelane_b32 v253, s22, 17
	s_cmp_eq_u32 s3, 2
	s_nop 0
	v_writelane_b32 v253, s23, 18
	s_cselect_b64 s[22:23], -1, 0
	v_writelane_b32 v253, s22, 19
	s_cmp_eq_u32 s3, 1
	s_nop 0
	v_writelane_b32 v253, s23, 20
	s_cselect_b64 s[22:23], -1, 0
	v_writelane_b32 v253, s22, 21
	s_cmp_eq_u32 s3, 0
	s_nop 0
	v_writelane_b32 v253, s23, 22
	s_cselect_b64 s[22:23], -1, 0
	s_lshl_b32 s3, s17, 2
	s_add_u32 s3, s14, s3
	v_writelane_b32 v253, s22, 23
	s_addc_u32 s14, s15, 0
	s_nop 0
;     __host__ __device__ bool next(int i, Unit& u) const {
;         const long L = (long)i * G + c; if (L >= nwg) return false;
;         int wgid = (int)L; { const int q = nwg / NXCD, r = nwg % NXCD, xcd = wgid % NXCD, off = wgid / NXCD; wgid = (xcd < r ? xcd * (q + 1) : r * (q + 1) + (xcd - r) * q) + off; }
;         const int nig = WGM * nN, gid = wgid / nig, fm = gid * WGM, gsz = (nM - fm) < WGM ? (nM - fm) : WGM;
;         u.pm = fm + ((wgid % nig) % gsz); u.pn = (wgid % nig) / gsz; return true;
; __global__ void __launch_bounds__(NTHR, 2) fwd_megakernel(Args args) {
;     ...
;             const abf* Qb = (const abf*)Z + 3 * CWD; const abf* Kb = (const abf*)Z + 4 * CWD;
;             constexpr int NQB = S / att::QB, NITEM = NH * (NQB / 2);
;             unsigned ord = 0u;
;             {   float ce[NH];
; #pragma unroll
;                 for (int h = 0; h < NH; ++h) ce[h] = cs[(size_t)h * S + S - 1];
	v_writelane_b32 v253, s23, 24
	s_add_u32 s22, s3, 0x1400
	s_addc_u32 s23, s14, 0
	v_writelane_b32 v253, s22, 25
	s_nop 1
	v_writelane_b32 v253, s23, 26
	s_add_u32 s22, s3, 0x2400
	s_addc_u32 s23, s14, 0
	v_writelane_b32 v253, s22, 27
	s_add_u32 s14, s68, 0x7400
	s_addc_u32 s15, s69, 0
	v_writelane_b32 v253, s23, 28
	v_writelane_b32 v253, s14, 29
	s_nop 1
	v_writelane_b32 v253, s15, 30
	s_add_u32 s14, s68, 0x7500
	s_addc_u32 s15, s69, 0
	v_writelane_b32 v253, s14, 31
	s_cmp_lt_i32 s2, 8
	s_nop 0
	v_writelane_b32 v253, s15, 32
	s_cselect_b64 s[14:15], -1, 0
	v_writelane_b32 v253, s14, 33
	s_ashr_i32 s3, s2, 31
	s_nop 0
	v_writelane_b32 v253, s15, 34
	s_lshl_b64 s[14:15], s[2:3], 2
	s_add_u32 s14, s18, s14
	v_writelane_b32 v253, s18, 35
	s_addc_u32 s15, s19, s15
	s_nop 0
	v_writelane_b32 v253, s19, 36
	v_writelane_b32 v253, s14, 37
	s_nop 1
	v_writelane_b32 v253, s15, 38
	s_lshl_b64 s[14:15], s[2:3], 16
	v_writelane_b32 v253, s20, 39
	s_add_u32 s14, s20, s14
	v_writelane_b32 v253, s21, 40
	s_addc_u32 s15, s21, s15
	v_writelane_b32 v253, s14, 41
	s_cmpk_lt_i32 s2, 0xa00
	s_nop 0
	v_writelane_b32 v253, s15, 42
	s_cselect_b64 s[14:15], -1, 0
	v_writelane_b32 v253, s14, 43
	s_ashr_i32 s33, s70, 31
	s_nop 0
	v_writelane_b32 v253, s15, 44
	s_lshr_b32 s14, s3, 29
	s_add_i32 s14, s2, s14
	s_ashr_i32 s15, s14, 3
	s_and_b32 s14, s14, -8
	s_sub_i32 s14, s2, s14
	s_add_u32 s17, s68, 0x8001800
	v_writelane_b32 v253, s17, 45
	s_addc_u32 s17, s69, 0
	v_writelane_b32 v253, s17, 46
	s_add_u32 s17, s68, 0x8002000
	v_writelane_b32 v253, s17, 47
	s_addc_u32 s17, s69, 0
	v_writelane_b32 v253, s17, 48
	s_add_u32 s17, s68, 0x8000
	v_writelane_b32 v253, s17, 49
	s_addc_u32 s17, s69, 0
	v_writelane_b32 v253, s17, 50
	s_ashr_i32 s17, s70, 3
	s_mul_i32 s17, s17, s14
	s_add_i32 s17, s17, s15
	s_and_b32 s18, s70, 7
	s_add_u32 s20, s68, 0x8003000
	s_addc_u32 s21, s69, 0
	v_writelane_b32 v253, s20, 51
	s_cmpk_lt_i32 s2, 0x200
	s_nop 0
	v_writelane_b32 v253, s21, 52
	s_cselect_b64 s[20:21], -1, 0
	v_writelane_b32 v253, s20, 53
	s_lshl_b32 s19, s14, 6
	s_nop 0
	v_writelane_b32 v253, s21, 54
	s_add_u32 s20, s68, 0x8004000
	s_addc_u32 s21, s69, 0
	v_writelane_b32 v253, s20, 55
	s_cmpk_lt_i32 s2, 0x800
	s_nop 0
	v_writelane_b32 v253, s21, 56
	s_cselect_b64 s[20:21], -1, 0
	v_writelane_b32 v253, s20, 57
	s_nop 1
	v_writelane_b32 v253, s21, 58
	s_lshl_b32 s20, s14, 8
	s_cmp_lt_i32 s14, 0
	s_mul_i32 s21, s14, 0x41
	s_cselect_b32 s19, s21, s19
	s_movk_i32 s21, 0x141
	s_cselect_b32 s21, s21, 0x140
	s_mul_i32 s21, s14, s21
	s_mulk_i32 s14, 0x101
	s_cselect_b32 s22, s14, s20
	s_add_i32 s21, s21, s15
	s_mul_hi_i32 s14, s21, 0x66666667
	s_lshr_b32 s20, s14, 31
	s_ashr_i32 s14, s14, 7
	s_add_i32 s14, s14, s20
	s_mul_i32 s20, s14, 0x140
	s_sub_i32 s20, s21, s20
	s_lshr_b32 s21, s20, 3
	s_lshl_b32 s21, s21, 1
	s_mov_b32 s23, s21
	s_and_b32 s20, s20, 7
	s_lshl_b32 s14, s14, 3
	s_add_i32 s44, s14, s20
	s_ashr_i32 s14, s21, 1
	v_writelane_b32 v253, s14, 59
	s_lshr_b32 s14, s21, 1
	s_add_u32 s20, s68, 0x18fffc
	s_addc_u32 s21, s69, 0
	v_writelane_b32 v253, s20, 60
	s_nop 1
	v_writelane_b32 v253, s21, 61
	s_add_u32 s20, s68, 0x19fffc
	s_addc_u32 s21, s69, 0
	v_writelane_b32 v253, s20, 62
	s_nop 1
	v_writelane_b32 v253, s21, 63
	s_add_u32 s20, s68, 0x1afffc
	s_addc_u32 s21, s69, 0
	v_writelane_b32 v254, s20, 0
	s_nop 1
	v_writelane_b32 v254, s21, 1
	s_add_u32 s20, s68, 0x1bfffc
	s_addc_u32 s21, s69, 0
	v_writelane_b32 v254, s20, 2
	s_nop 1
	v_writelane_b32 v254, s21, 3
	s_add_u32 s20, s68, 0x1cfffc
	s_addc_u32 s21, s69, 0
	v_writelane_b32 v254, s20, 4
	s_nop 1
	v_writelane_b32 v254, s21, 5
	s_add_u32 s20, s68, 0x1dfffc
	s_addc_u32 s21, s69, 0
	v_writelane_b32 v254, s20, 6
	s_nop 1
	v_writelane_b32 v254, s21, 7
	s_add_u32 s20, s68, 0x1efffc
	s_addc_u32 s21, s69, 0
	v_writelane_b32 v254, s20, 8
	s_nop 1
	v_writelane_b32 v254, s21, 9
	s_add_u32 s20, s68, 0x1ffffc
	s_addc_u32 s21, s69, 0
	v_writelane_b32 v254, s20, 10
	s_cmp_eq_u32 s18, 0
	s_cselect_b32 s17, s17, s2
	v_writelane_b32 v254, s21, 11
	v_writelane_b32 v254, s17, 12
	s_add_i32 s17, s19, s15
	s_ashr_i32 s18, s17, 31
	s_lshr_b32 s18, s18, 28
	s_add_i32 s18, s17, s18
	s_and_b32 s19, s18, 0xfff0
	s_sub_i32 s17, s17, s19
	s_bfe_u32 s19, s17, 0x10007
	s_add_i32 s19, s17, s19
	s_and_b32 s20, s19, 0xfe
	s_sub_i32 s17, s17, s20
	s_ashr_i32 s18, s18, 4
	s_bfe_i32 s19, s19, 0x80000
	s_lshl_b32 s18, s18, 1
	s_sext_i32_i16 s19, s19
	s_sext_i32_i8 s17, s17
	s_add_i32 s46, s18, s17
	s_lshr_b32 s18, s19, 1
	s_ashr_i32 s47, s46, 31
	s_bfe_i64 s[40:41], s[18:19], 0x100000
	s_ashr_i32 s17, s19, 1
	s_lshl_b64 s[18:19], s[46:47], 19
	s_lshl_b64 s[20:21], s[40:41], 19
	v_writelane_b32 v254, s17, 13
	s_add_u32 s48, s28, s20
	v_writelane_b32 v254, s28, 14
	s_addc_u32 s49, s29, s21
	s_mov_b64 s[68:69], 0x80
	v_writelane_b32 v254, s29, 15
	s_add_u32 s28, s48, 0x40000
	s_addc_u32 s29, s49, 0
	v_writelane_b32 v254, s28, 16
	s_nop 1
	v_writelane_b32 v254, s29, 17
	s_add_u32 s28, s8, s18
	s_addc_u32 s29, s9, s19
	s_add_u32 s50, s28, 0x40000
	v_writelane_b32 v254, s28, 18
	s_addc_u32 s51, s29, 0
	s_nop 0
	v_writelane_b32 v254, s29, 19
	v_writelane_b32 v254, s50, 20
	s_add_u32 s28, s48, 0x40080
	s_nop 0
	v_writelane_b32 v254, s51, 21
	v_writelane_b32 v254, s48, 22
	s_addc_u32 s29, s49, 0
	s_add_u32 s20, s30, s20
	v_writelane_b32 v254, s49, 23
	v_writelane_b32 v254, s28, 24
	s_nop 1
	v_writelane_b32 v254, s29, 25
	v_writelane_b32 v254, s30, 26
	s_addc_u32 s21, s31, s21
	s_add_u32 s28, s20, 0x40000
	v_writelane_b32 v254, s31, 27
	s_addc_u32 s29, s21, 0
	v_writelane_b32 v254, s28, 28
	s_add_u32 s18, s42, s18
	s_addc_u32 s19, s43, s19
	v_writelane_b32 v254, s29, 29
; #define PG8_WAIT_V(n) asm volatile("s_waitcnt vmcnt(" #n ")" ::: "memory")
; #define PG8_BAR __builtin_amdgcn_s_barrier()
;     __host__ __device__ bool next(int i, Unit& u) const {
;     ...
;         int wgid = (int)L; { const int q = nwg / NXCD, r = nwg % NXCD, xcd = wgid % NXCD, off = wgid / NXCD; wgid = (xcd < r ? xcd * (q + 1) : r * (q + 1) + (xcd - r) * q) + off; }
;         const int nig = WGM * nN, gid = wgid / nig, fm = gid * WGM, gsz = (nM - fm) < WGM ? (nM - fm) : WGM;
;         u.pm = fm + ((wgid % nig) % gsz); u.pn = (wgid % nig) / gsz; return true;
; template <class Epi, class Sched, bool ALIGN_EPI = false, bool SP2 = false>
; __device__ __forceinline__ void gemm_phase(PG8_LAS unsigned char* lds, const Gemm g, const Sched& S, const Epi& E) {
;     ...
;     const char* cA = (const char*)g.A + (size_t)cur.pm * tstepA; const char* cB = (const char*)g.Bt + (size_t)cur.pn * tstepB;
;     S.a_ready(cur);
;     if constexpr (SP2) {
;         PG8_STAGE(PG8_SB(0, 0), cB, voffB); PG8_STAGE(PG8_SB(0, 1), cB + hstepB, voffB); PG8_STAGE(PG8_SA(0, 0), cA, voffA); PG8_STAGE(PG8_SA(0, 1), cA + hstepA, voffA);
;         if (wr == 1) PG8_BAR;
;         PG8_WAIT_V(2); PG8_BAR;
;         PG8_STAGE(PG8_SB(1, 0), cB + kstep, voffB); PG8_STAGE(PG8_SA(1, 0), cA + kstep, voffA); PG8_STAGE(PG8_SB(1, 1), cB + hstepB + kstep, voffB);
;         PG8_WAIT_V(6); PG8_BAR;
;     } else {
;         PG8_STAGE(PG8_SB(0, 0), cB, voffB); PG8_STAGE(PG8_SA(0, 0), cA, voffA); PG8_STAGE(PG8_SB(0, 1), cB + hstepB, voffB); PG8_STAGE(PG8_SA(0, 1), cA + hstepA, voffA);
;         if (wr == 1) PG8_BAR;
;         PG8_WAIT_V(4); PG8_BAR;
;         PG8_STAGE(PG8_SB(1, 0), cB + kstep, voffB); PG8_STAGE(PG8_SA(1, 0), cA + kstep, voffA); PG8_STAGE(PG8_SB(1, 1), cB + hstepB + kstep, voffB);
;         PG8_WAIT_V(6); PG8_BAR;
;     }
;     for (;;) {
;         const bool has_next = S.next(ui + 1, nxt);
;         const char* nA = has_next ? (const char*)g.A + (size_t)nxt.pm * tstepA : cA; const char* nB = has_next ? (const char*)g.Bt + (size_t)nxt.pn * tstepB : cB;
;         for (int t = 0; t < nt; t += 2) {
;             const bool last = (t == nt - 2);
;             const char* a1 = cA + (size_t)(t + 1) * kstep;
;             const char* a2 = last ? nA : cA + (size_t)(t + 2) * kstep; const char* b2 = last ? nB : cB + (size_t)(t + 2) * kstep;
;             const char* a3 = a2 + kstep; const char* b3 = b2 + kstep;
	v_writelane_b32 v254, s42, 30
	v_writelane_b32 v254, s43, 31
	s_add_u32 s28, s18, 0x40000
	v_writelane_b32 v254, s18, 32
	s_addc_u32 s29, s19, 0
	s_nop 0
	v_writelane_b32 v254, s19, 33
	v_writelane_b32 v254, s28, 34
	s_add_u32 s18, s20, 0x40080
	s_nop 0
	v_writelane_b32 v254, s29, 35
	v_writelane_b32 v254, s20, 36
	s_addc_u32 s19, s21, 0
	s_add_i32 s15, s22, s15
	s_ashr_i32 s17, s15, 31
	v_writelane_b32 v254, s21, 37
	s_lshr_b32 s17, s17, 24
	v_writelane_b32 v254, s18, 38
	s_add_i32 s17, s15, s17
	s_mov_b32 s28, s87
	v_writelane_b32 v254, s19, 39
	s_and_b32 s18, s17, 0xff00
	s_sub_i32 s15, s15, s18
	s_lshr_b32 s18, s15, 3
	s_lshl_b32 s18, s18, 1
	s_mov_b32 s19, s18
	s_and_b32 s15, s15, 7
	s_ashr_i32 s17, s17, 8
	s_nop 0
	s_lshl_b32 s17, s17, 3
	s_nop 0
	s_nop 0
	s_add_i32 s22, s17, s15
	s_ashr_i32 s15, s18, 1
	v_writelane_b32 v254, s15, 40
	s_lshr_b32 s18, s18, 1
	s_mov_b32 s20, s22
	s_ashr_i32 s23, s22, 31
	s_bfe_i64 s[18:19], s[18:19], 0x100000
	v_writelane_b32 v254, s20, 41
	s_lshl_b64 s[18:19], s[18:19], 20
	s_nop 0
	v_writelane_b32 v254, s21, 42
	s_lshl_b64 s[20:21], s[22:23], 20
	s_add_u32 s18, s36, s18
	s_addc_u32 s19, s37, s19
	s_add_u32 s22, s18, 0x80000
	s_addc_u32 s23, s19, 0
	v_writelane_b32 v254, s22, 43
	s_add_u32 s20, s10, s20
	s_addc_u32 s21, s11, s21
	v_writelane_b32 v254, s23, 44
	s_add_u32 s22, s20, 0x80000
	v_writelane_b32 v254, s20, 45
	s_addc_u32 s23, s21, 0
	s_nop 0
	v_writelane_b32 v254, s21, 46
	v_writelane_b32 v254, s22, 47
	s_add_u32 s20, s18, 0x80080
	s_nop 0
	v_writelane_b32 v254, s23, 48
	v_writelane_b32 v254, s18, 49
	s_addc_u32 s21, s19, 0
	s_nop 0
	v_writelane_b32 v254, s19, 50
	v_writelane_b32 v254, s20, 51
	s_lshl_b64 s[18:19], s[46:47], 22
	s_nop 0
	v_writelane_b32 v254, s21, 52
	s_lshl_b64 s[20:21], s[40:41], 22
	s_add_u32 s20, s38, s20
	v_writelane_b32 v254, s38, 53
	s_addc_u32 s21, s39, s21
	s_add_u32 s22, s20, 0x200000
	v_writelane_b32 v254, s39, 54
	s_addc_u32 s23, s21, 0
	v_writelane_b32 v254, s22, 55
	s_add_u32 s18, s4, s18
	s_addc_u32 s19, s5, s19
	v_writelane_b32 v254, s23, 56
	s_add_u32 s22, s18, 0x200000
	v_writelane_b32 v254, s18, 57
	s_addc_u32 s23, s19, 0
	s_movk_i32 s39, 0xbfff
	v_writelane_b32 v254, s19, 58
	v_writelane_b32 v254, s22, 59
	s_add_u32 s18, s20, 0x200080
	s_nop 0
	v_writelane_b32 v254, s23, 60
	v_writelane_b32 v254, s20, 61
	s_addc_u32 s19, s21, 0
	s_ashr_i32 s45, s44, 31
	v_writelane_b32 v254, s21, 62
	v_writelane_b32 v254, s18, 63
	s_bfe_i64 s[14:15], s[14:15], 0x100000
	s_lshl_b64 s[14:15], s[14:15], 20
	v_writelane_b32 v255, s19, 0
	s_mov_b32 s18, s44
	v_writelane_b32 v255, s18, 1
	s_nop 1
	v_writelane_b32 v255, s19, 2
	s_lshl_b64 s[18:19], s[44:45], 20
	s_add_u32 s14, s26, s14
	v_writelane_b32 v255, s26, 3
	s_addc_u32 s15, s27, s15
	s_add_u32 s20, s14, 0x80000
	v_writelane_b32 v255, s27, 4
	s_addc_u32 s21, s15, 0
	v_writelane_b32 v255, s20, 5
	s_add_u32 s18, s6, s18
	s_addc_u32 s19, s7, s19
	v_writelane_b32 v255, s21, 6
	s_add_u32 s20, s18, 0x80000
	v_writelane_b32 v255, s18, 7
	s_addc_u32 s21, s19, 0
	s_nop 0
	v_writelane_b32 v255, s19, 8
	v_writelane_b32 v255, s20, 9
	s_add_u32 s18, s14, 0x80080
	s_nop 0
	v_writelane_b32 v255, s21, 10
	v_writelane_b32 v255, s14, 11
	s_addc_u32 s19, s15, 0
	s_nop 0
	v_writelane_b32 v255, s15, 12
	v_writelane_b32 v255, s18, 13
	s_lshl_b64 s[14:15], s[40:41], 20
	s_nop 0
	v_writelane_b32 v255, s19, 14
	s_mov_b32 s18, s46
	v_writelane_b32 v255, s18, 15
	s_nop 1
	v_writelane_b32 v255, s19, 16
	s_lshl_b64 s[18:19], s[46:47], 20
	s_add_u32 s20, s34, s14
	v_writelane_b32 v255, s34, 17
	s_addc_u32 s21, s35, s15
	s_add_u32 s14, s20, 0x80000
	v_writelane_b32 v255, s35, 18
	s_addc_u32 s15, s21, 0
	v_writelane_b32 v255, s14, 19
	s_add_u32 s18, s6, s18
	s_addc_u32 s19, s7, s19
	v_writelane_b32 v255, s15, 20
	s_movk_i32 s14, 0x3ff
	v_and_or_b32 v0, v0, s14, v202
	s_add_u32 s14, s18, 0x80000
	v_writelane_b32 v255, s18, 21
	s_addc_u32 s15, s19, 0
	s_mov_b64 s[34:35], 0x2000
	v_writelane_b32 v255, s19, 22
	v_writelane_b32 v255, s14, 23
	s_nop 1
	v_writelane_b32 v255, s15, 24
	s_add_u32 s14, s20, 0x80080
	v_writelane_b32 v255, s20, 25
	s_addc_u32 s15, s21, 0
	s_nop 0
	v_writelane_b32 v255, s21, 26
	v_writelane_b32 v255, s14, 27
	s_nop 1
	v_writelane_b32 v255, s15, 28
	s_abs_i32 s14, s70
	s_sub_i32 s15, 1, s14
	s_cmp_lt_u32 s14, 2
	s_cselect_b32 s15, s15, 1
	s_sub_i32 s16, s15, s14
	s_cmp_ge_u32 s15, s14
	s_cselect_b32 s14, s16, s15
	s_cmp_eq_u32 s2, s14
	s_cselect_b64 s[14:15], -1, 0
	v_writelane_b32 v255, s14, 29
	s_lshl_b32 s22, s70, 10
	s_add_i32 s38, 0, 0x20808
	v_writelane_b32 v255, s15, 30
	s_lshl_b32 s14, s2, 8
	s_lshl_b32 s15, s97, 5
	s_add_i32 s14, s14, s15
	v_writelane_b32 v255, s14, 31
	s_lshl_b32 s14, s2, 10
	v_writelane_b32 v255, s14, 32
	s_lshl_b32 s14, s70, 8
	v_writelane_b32 v255, s14, 33
	s_add_i32 s14, s24, 0xa800
	v_writelane_b32 v255, s14, 34
	s_add_i32 s14, s24, 0xc800
	v_writelane_b32 v255, s14, 35
	s_add_i32 s14, s24, 0xd000
	v_writelane_b32 v255, s14, 36
	s_add_i32 s14, s24, 0xd400
	v_writelane_b32 v255, s14, 37
	s_mov_b32 s14, s24
	v_writelane_b32 v255, s14, 38
	s_nop 1
	v_writelane_b32 v255, s15, 39
	s_add_i32 s14, s24, 0xd800
	v_writelane_b32 v255, s14, 40
	s_add_i32 s14, 0, 0x20840
	v_writelane_b32 v255, s14, 41
	s_add_i32 s14, 0, 0x20844
	v_writelane_b32 v255, s14, 42
	s_add_i32 s14, 0, 0x20800
	v_writelane_b32 v255, s14, 43
	s_add_i32 s14, 0, 0x2080c
	v_writelane_b32 v255, s14, 44
	s_add_i32 s14, 0, 0x20804
	v_writelane_b32 v255, s14, 45
	v_cmp_eq_u32_e64 s[14:15], 0, v0
	s_nop 1
	v_writelane_b32 v255, s14, 46
	s_nop 1
	v_writelane_b32 v255, s15, 47
	v_writelane_b32 v255, s56, 48
	s_mov_b64 s[14:15], -1
	s_nop 0
	v_writelane_b32 v255, s57, 49
	v_writelane_b32 v255, s97, 50
	v_writelane_b32 v255, s36, 51
	s_nop 1
	v_writelane_b32 v255, s37, 52
	v_writelane_b32 v255, s22, 53
	s_branch .LBB0_8

;     __host__ __device__ bool next(int i, Unit& u) const {
;         const long L = (long)i * G + c; if (L >= nwg) return false;
;         int wgid = (int)L; { const int q = nwg / NXCD, r = nwg % NXCD, xcd = wgid % NXCD, off = wgid / NXCD; wgid = (xcd < r ? xcd * (q + 1) : r * (q + 1) + (xcd - r) * q) + off; }
;         const int nig = WGM * nN, gid = wgid / nig, fm = gid * WGM, gsz = (nM - fm) < WGM ? (nM - fm) : WGM;
;         u.pm = fm + ((wgid % nig) % gsz); u.pn = (wgid % nig) / gsz; return true;
.LBB0_153:
	s_add_i32 s97, s97, 1
	s_mul_i32 s15, s97, s33
	s_mul_hi_u32 s24, s97, s70
	s_add_i32 s24, s24, s15
	s_mul_i32 s15, s97, s70
	s_add_u32 s54, s15, s2
	s_addc_u32 s55, s24, s3
	v_mov_b64_e32 v[0:1], 0xa00
	v_cmp_lt_i64_e64 s[42:43], s[54:55], v[0:1]
	v_mov_b64_e32 v[0:1], 0x9ff
	v_cmp_gt_i64_e32 vcc, s[54:55], v[0:1]
	s_cbranch_vccnz .LBB0_155
	s_ashr_i32 s14, s54, 31
	s_lshr_b32 s14, s14, 29
	s_add_i32 s14, s54, s14
	s_ashr_i32 s15, s14, 3
	s_and_b32 s14, s14, -8
	s_sub_i32 s14, s54, s14
	s_cmp_lt_i32 s14, 0
	s_movk_i32 s24, 0x141
	s_cselect_b32 s24, s24, 0x140
	s_mul_i32 s14, s14, s24
	s_add_i32 s14, s14, s15
	s_mul_hi_i32 s15, s14, 0x66666667
	s_lshr_b32 s24, s15, 31
	s_ashr_i32 s15, s15, 7
	s_add_i32 s15, s15, s24
	s_lshl_b32 s24, s15, 3
	s_sub_i32 s25, 64, s24
	s_min_i32 s25, s25, 8
	s_abs_i32 s26, s25
	v_cvt_f32_u32_e32 v0, s26
	s_sub_i32 s28, 0, s26
	s_mulk_i32 s15, 0x140
	s_sub_i32 s14, s14, s15
	v_rcp_iflag_f32_e32 v0, v0
	s_abs_i32 s15, s14
	s_xor_b32 s27, s14, s25
	s_ashr_i32 s27, s27, 31
	v_mul_f32_e32 v0, 0x4f7ffffe, v0
	v_cvt_u32_f32_e32 v0, v0
	s_nop 0
	v_readfirstlane_b32 s29, v0
	s_mul_i32 s28, s28, s29
	s_mul_hi_u32 s28, s29, s28
	s_add_i32 s29, s29, s28
	s_mul_hi_u32 s28, s15, s29
	s_mul_i32 s29, s28, s26
	s_sub_i32 s15, s15, s29
	s_add_i32 s30, s28, 1
	s_sub_i32 s29, s15, s26
	s_cmp_ge_u32 s15, s26
	s_cselect_b32 s28, s30, s28
	s_cselect_b32 s15, s29, s15
	s_add_i32 s29, s28, 1
	s_cmp_ge_u32 s15, s26
	s_cselect_b32 s15, s29, s28
	s_xor_b32 s15, s15, s27
	s_sub_i32 s62, s15, s27
	s_mul_i32 s15, s62, s25
	s_sub_i32 s14, s14, s15
	s_add_i32 s14, s24, s14

;     __host__ __device__ bool next(int i, Unit& u) const {
;     ...
;         const int nig = WGM * nN, gid = wgid / nig, fm = gid * WGM, gsz = (nM - fm) < WGM ? (nM - fm) : WGM;
;         u.pm = fm + ((wgid % nig) % gsz); u.pn = (wgid % nig) / gsz; return true;
.LBB0_770:
	s_ashr_i32 s24, s24, 3
	s_add_i32 s24, s46, s24
	s_ashr_i32 s25, s24, 31
	s_lshr_b32 s25, s25, 24
	s_add_i32 s25, s24, s25
	s_ashr_i32 s26, s25, 8
	s_lshl_b32 s26, s26, 3
	s_sub_i32 s27, 64, s26
	s_min_i32 s27, s27, 8
	s_abs_i32 s28, s27
	v_cvt_f32_u32_e32 v0, s28
	s_sub_i32 s30, 0, s28
	s_andn2_b32 s25, s25, 255
	s_sub_i32 s24, s24, s25
	v_rcp_iflag_f32_e32 v0, v0
	s_abs_i32 s25, s24
	s_xor_b32 s29, s24, s27
	s_ashr_i32 s29, s29, 31
	v_mul_f32_e32 v0, 0x4f7ffffe, v0
	v_cvt_u32_f32_e32 v0, v0
	s_nop 0
	v_readfirstlane_b32 s31, v0
	s_mul_i32 s30, s30, s31
	s_mul_hi_u32 s30, s31, s30
	s_add_i32 s31, s31, s30
	s_mul_hi_u32 s30, s25, s31
	s_mul_i32 s31, s30, s28
	s_sub_i32 s25, s25, s31
	s_add_i32 s44, s30, 1
	s_sub_i32 s31, s25, s28
	s_cmp_ge_u32 s25, s28
	s_cselect_b32 s30, s44, s30
	s_cselect_b32 s25, s31, s25
	s_add_i32 s31, s30, 1
	s_cmp_ge_u32 s25, s28
	s_cselect_b32 s25, s31, s30
	s_xor_b32 s25, s25, s29
	s_sub_i32 s44, s25, s29
	s_mul_i32 s25, s44, s27
	s_sub_i32 s24, s24, s25
	s_add_i32 s46, s26, s24
